# P2: two late weight-conversion tiles per item on the four waves that wait for the WY solve
# baseline (speedup 1.0000x reference)
.LBB0_360:
	s_or_b64 exec, exec, s[4:5]
	s_waitcnt lgkmcnt(0)
	s_barrier
	s_and_saveexec_b64 s[4:5], s[44:45]
	s_xor_b64 s[4:5], exec, s[4:5]
	s_cbranch_execz .LBB0_373
	ds_read_b32 v16, v131
	v_lshl_add_u64 v[0:1], s[96:97], 0, v[76:77]
	v_lshl_add_u64 v[18:19], v[0:1], 0, v[78:79]
	ds_read_b128 v[0:3], v183
	ds_read_b128 v[4:7], v183 offset:16
	ds_read_b128 v[8:11], v183 offset:32
	ds_read_b128 v[12:15], v183 offset:48
	s_mov_b64 s[6:7], 0x4400
	s_waitcnt lgkmcnt(3)
	v_lshlrev_b32_e32 v22, 16, v0
	v_and_b32_e32 v23, 0xffff0000, v0
	v_pk_mul_f32 v[22:23], v[16:17], v[22:23] op_sel_hi:[0,1]
	v_cvt_pk_bf16_f32 v0, v22, v23
	v_lshlrev_b32_e32 v22, 16, v1
	v_and_b32_e32 v23, 0xffff0000, v1
	v_pk_mul_f32 v[22:23], v[16:17], v[22:23] op_sel_hi:[0,1]
	v_cvt_pk_bf16_f32 v1, v22, v23
	v_lshlrev_b32_e32 v22, 16, v2
	v_and_b32_e32 v23, 0xffff0000, v2
	v_pk_mul_f32 v[22:23], v[16:17], v[22:23] op_sel_hi:[0,1]
	v_lshl_add_u64 v[20:21], v[18:19], 0, s[6:7]
	v_cvt_pk_bf16_f32 v2, v22, v23
	v_lshlrev_b32_e32 v22, 16, v3
	v_and_b32_e32 v23, 0xffff0000, v3
	s_movk_i32 s6, 0x4000
	v_pk_mul_f32 v[22:23], v[16:17], v[22:23] op_sel_hi:[0,1]
	v_add_co_u32_e32 v18, vcc, s6, v18
	v_cvt_pk_bf16_f32 v3, v22, v23
	s_nop 0
	v_addc_co_u32_e32 v19, vcc, 0, v19, vcc
	global_store_dwordx4 v[18:19], v[0:3], off offset:1024
	s_mov_b64 s[6:7], 0xac00
	s_waitcnt lgkmcnt(2)
	v_lshlrev_b32_e32 v0, 16, v4
	v_and_b32_e32 v1, 0xffff0000, v4
	v_lshlrev_b32_e32 v2, 16, v5
	v_and_b32_e32 v3, 0xffff0000, v5
	v_pk_mul_f32 v[0:1], v[16:17], v[0:1] op_sel_hi:[0,1]
	v_pk_mul_f32 v[2:3], v[16:17], v[2:3] op_sel_hi:[0,1]
	v_cvt_pk_bf16_f32 v0, v0, v1
	v_cvt_pk_bf16_f32 v1, v2, v3
	v_lshlrev_b32_e32 v2, 16, v6
	v_and_b32_e32 v3, 0xffff0000, v6
	v_lshlrev_b32_e32 v4, 16, v7
	v_and_b32_e32 v5, 0xffff0000, v7
	v_pk_mul_f32 v[2:3], v[16:17], v[2:3] op_sel_hi:[0,1]
	v_pk_mul_f32 v[4:5], v[16:17], v[4:5] op_sel_hi:[0,1]
	v_cvt_pk_bf16_f32 v2, v2, v3
	v_cvt_pk_bf16_f32 v3, v4, v5
	global_store_dwordx4 v[20:21], v[0:3], off offset:16
	s_waitcnt lgkmcnt(1)
	v_lshlrev_b32_e32 v4, 16, v11
	v_and_b32_e32 v5, 0xffff0000, v11
	v_lshlrev_b32_e32 v0, 16, v8
	v_and_b32_e32 v1, 0xffff0000, v8
	v_lshlrev_b32_e32 v2, 16, v9
	v_and_b32_e32 v3, 0xffff0000, v9
	v_pk_mul_f32 v[0:1], v[16:17], v[0:1] op_sel_hi:[0,1]
	v_pk_mul_f32 v[2:3], v[16:17], v[2:3] op_sel_hi:[0,1]
	v_cvt_pk_bf16_f32 v0, v0, v1
	v_cvt_pk_bf16_f32 v1, v2, v3
	v_lshlrev_b32_e32 v2, 16, v10
	v_and_b32_e32 v3, 0xffff0000, v10
	v_pk_mul_f32 v[2:3], v[16:17], v[2:3] op_sel_hi:[0,1]
	v_pk_mul_f32 v[4:5], v[16:17], v[4:5] op_sel_hi:[0,1]
	v_cvt_pk_bf16_f32 v2, v2, v3
	v_cvt_pk_bf16_f32 v3, v4, v5
	global_store_dwordx4 v[20:21], v[0:3], off offset:32
	s_waitcnt lgkmcnt(0)
	v_lshlrev_b32_e32 v4, 16, v15
	v_and_b32_e32 v5, 0xffff0000, v15
	v_lshlrev_b32_e32 v0, 16, v12
	v_and_b32_e32 v1, 0xffff0000, v12
	v_lshlrev_b32_e32 v2, 16, v13
	v_and_b32_e32 v3, 0xffff0000, v13
	v_pk_mul_f32 v[0:1], v[16:17], v[0:1] op_sel_hi:[0,1]
	v_pk_mul_f32 v[2:3], v[16:17], v[2:3] op_sel_hi:[0,1]
	v_cvt_pk_bf16_f32 v0, v0, v1
	v_cvt_pk_bf16_f32 v1, v2, v3
	v_lshlrev_b32_e32 v2, 16, v14
	v_and_b32_e32 v3, 0xffff0000, v14
	v_pk_mul_f32 v[2:3], v[16:17], v[2:3] op_sel_hi:[0,1]
	v_pk_mul_f32 v[4:5], v[16:17], v[4:5] op_sel_hi:[0,1]
	v_cvt_pk_bf16_f32 v2, v2, v3
	v_cvt_pk_bf16_f32 v3, v4, v5
	global_store_dwordx4 v[20:21], v[0:3], off offset:48
	s_nop 1
	v_lshl_add_u64 v[0:1], s[96:97], 0, v[82:83]
	v_lshl_add_u64 v[6:7], v[0:1], 0, v[84:85]
	ds_read_u16 v0, v172
	ds_read_u16 v1, v172 offset:272
	v_lshl_add_u64 v[4:5], v[6:7], 0, s[6:7]
	s_mov_b32 s6, 0xa000
	v_add_co_u32_e32 v6, vcc, s6, v6
	s_waitcnt lgkmcnt(0)
	v_lshlrev_b32_e32 v9, 16, v1
	v_lshlrev_b32_e32 v8, 16, v0
	ds_read_b128 v[0:3], v157
	v_addc_co_u32_e32 v7, vcc, 0, v7, vcc
	s_waitcnt lgkmcnt(0)
	v_pk_mul_f32 v[8:9], v[0:1], v[8:9]
	ds_read_u16 v0, v173
	ds_read_u16 v1, v172 offset:816
	s_waitcnt lgkmcnt(1)
	v_lshlrev_b32_e32 v0, 16, v0
	s_waitcnt lgkmcnt(0)
	v_lshlrev_b32_e32 v1, 16, v1
	v_pk_mul_f32 v[10:11], v[2:3], v[0:1]
	ds_read_u16 v0, v173 offset:544
	ds_read_u16 v1, v172 offset:1360
	s_waitcnt lgkmcnt(1)
	v_lshlrev_b32_e32 v12, 16, v0
	s_waitcnt lgkmcnt(0)
	v_lshlrev_b32_e32 v13, 16, v1
	ds_read_b128 v[0:3], v158
	s_waitcnt lgkmcnt(0)
	v_pk_mul_f32 v[12:13], v[0:1], v[12:13]
	ds_read_u16 v0, v173 offset:1088
	ds_read_u16 v1, v172 offset:1904
	s_waitcnt lgkmcnt(1)
	v_lshlrev_b32_e32 v0, 16, v0
	s_waitcnt lgkmcnt(0)
	v_lshlrev_b32_e32 v1, 16, v1
	v_pk_mul_f32 v[14:15], v[2:3], v[0:1]
	v_cvt_pk_bf16_f32 v0, v8, v9
	v_cvt_pk_bf16_f32 v1, v10, v11
	v_cvt_pk_bf16_f32 v2, v12, v13
	v_cvt_pk_bf16_f32 v3, v14, v15
	global_store_dwordx4 v[6:7], v[0:3], off offset:3072
	ds_read_u16 v0, v173 offset:1632
	ds_read_u16 v1, v172 offset:2448
	s_waitcnt lgkmcnt(1)
	v_lshlrev_b32_e32 v6, 16, v0
	s_waitcnt lgkmcnt(0)
	v_lshlrev_b32_e32 v7, 16, v1
	ds_read_b128 v[0:3], v159
	s_waitcnt lgkmcnt(0)
	v_pk_mul_f32 v[6:7], v[0:1], v[6:7]
	ds_read_u16 v0, v173 offset:2176
	ds_read_u16 v1, v172 offset:2992
	s_waitcnt lgkmcnt(1)
	v_lshlrev_b32_e32 v0, 16, v0
	s_waitcnt lgkmcnt(0)
	v_lshlrev_b32_e32 v1, 16, v1
	v_pk_mul_f32 v[8:9], v[2:3], v[0:1]
	ds_read_u16 v0, v173 offset:2720
	ds_read_u16 v1, v172 offset:3536
	s_waitcnt lgkmcnt(1)
	v_lshlrev_b32_e32 v10, 16, v0
	s_waitcnt lgkmcnt(0)
	v_lshlrev_b32_e32 v11, 16, v1
	ds_read_b128 v[0:3], v160
	s_waitcnt lgkmcnt(0)
	v_pk_mul_f32 v[10:11], v[0:1], v[10:11]
	ds_read_u16 v0, v173 offset:3264
	ds_read_u16 v1, v172 offset:4080
	s_waitcnt lgkmcnt(1)
	v_lshlrev_b32_e32 v0, 16, v0
	s_waitcnt lgkmcnt(0)
	v_lshlrev_b32_e32 v1, 16, v1
	v_pk_mul_f32 v[12:13], v[2:3], v[0:1]
	v_cvt_pk_bf16_f32 v0, v6, v7
	v_cvt_pk_bf16_f32 v1, v8, v9
	v_cvt_pk_bf16_f32 v2, v10, v11
	v_cvt_pk_bf16_f32 v3, v12, v13
	global_store_dwordx4 v[4:5], v[0:3], off offset:16
	ds_read_u16 v0, v173 offset:3808
	ds_read_u16 v1, v172 offset:4624
	s_waitcnt lgkmcnt(1)
	v_lshlrev_b32_e32 v6, 16, v0
	s_waitcnt lgkmcnt(0)
	v_lshlrev_b32_e32 v7, 16, v1
	ds_read_b128 v[0:3], v161
	s_waitcnt lgkmcnt(0)
	v_pk_mul_f32 v[6:7], v[0:1], v[6:7]
	ds_read_u16 v0, v173 offset:4352
	ds_read_u16 v1, v172 offset:5168
	s_waitcnt lgkmcnt(1)
	v_lshlrev_b32_e32 v0, 16, v0
	s_waitcnt lgkmcnt(0)
	v_lshlrev_b32_e32 v1, 16, v1
	v_pk_mul_f32 v[8:9], v[2:3], v[0:1]
	ds_read_u16 v0, v173 offset:4896
	ds_read_u16 v1, v172 offset:5712
	s_waitcnt lgkmcnt(1)
	v_lshlrev_b32_e32 v10, 16, v0
	s_waitcnt lgkmcnt(0)
	v_lshlrev_b32_e32 v11, 16, v1
	ds_read_b128 v[0:3], v162
	s_waitcnt lgkmcnt(0)
	v_pk_mul_f32 v[10:11], v[0:1], v[10:11]
	ds_read_u16 v0, v173 offset:5440
	ds_read_u16 v1, v172 offset:6256
	s_waitcnt lgkmcnt(1)
	v_lshlrev_b32_e32 v0, 16, v0
	s_waitcnt lgkmcnt(0)
	v_lshlrev_b32_e32 v1, 16, v1
	v_pk_mul_f32 v[12:13], v[2:3], v[0:1]
	v_cvt_pk_bf16_f32 v0, v6, v7
	v_cvt_pk_bf16_f32 v1, v8, v9
	v_cvt_pk_bf16_f32 v2, v10, v11
	v_cvt_pk_bf16_f32 v3, v12, v13
	global_store_dwordx4 v[4:5], v[0:3], off offset:32
	ds_read_u16 v0, v173 offset:5984
	ds_read_u16 v1, v172 offset:6800
	s_waitcnt lgkmcnt(1)
	v_lshlrev_b32_e32 v6, 16, v0
	s_waitcnt lgkmcnt(0)
	v_lshlrev_b32_e32 v7, 16, v1
	ds_read_b128 v[0:3], v163
	s_waitcnt lgkmcnt(0)
	v_pk_mul_f32 v[6:7], v[0:1], v[6:7]
	ds_read_u16 v0, v173 offset:6528
	ds_read_u16 v1, v172 offset:7344
	v_cvt_pk_bf16_f32 v6, v6, v7
	s_waitcnt lgkmcnt(1)
	v_lshlrev_b32_e32 v0, 16, v0
	s_waitcnt lgkmcnt(0)
	v_lshlrev_b32_e32 v1, 16, v1
	v_pk_mul_f32 v[8:9], v[2:3], v[0:1]
	ds_read_u16 v0, v173 offset:7072
	ds_read_u16 v1, v172 offset:7888
	v_cvt_pk_bf16_f32 v7, v8, v9
	s_waitcnt lgkmcnt(1)
	v_lshlrev_b32_e32 v10, 16, v0
	s_waitcnt lgkmcnt(0)
	v_lshlrev_b32_e32 v11, 16, v1
	ds_read_b128 v[0:3], v164
	s_waitcnt lgkmcnt(0)
	v_pk_mul_f32 v[0:1], v[0:1], v[10:11]
	ds_read_u16 v10, v173 offset:7616
	ds_read_u16 v11, v172 offset:8432
	v_cvt_pk_bf16_f32 v8, v0, v1
	v_mov_b32_e32 v0, 0
	s_waitcnt lgkmcnt(1)
	v_lshlrev_b32_e32 v10, 16, v10
	s_waitcnt lgkmcnt(0)
	v_lshlrev_b32_e32 v11, 16, v11
	v_pk_mul_f32 v[2:3], v[2:3], v[10:11]
	s_nop 0
	v_cvt_pk_bf16_f32 v9, v2, v3
	global_store_dwordx4 v[4:5], v[6:9], off offset:48
	s_mov_b32 s98, 0
.Lcv2_again:
	v_mov_b32_e32 v0, 0
	s_and_saveexec_b64 s[6:7], s[42:43]
	s_cbranch_execz .LBB0_365
	s_mov_b64 s[10:11], exec
	v_mbcnt_lo_u32_b32 v0, s10, 0
	v_mbcnt_hi_u32_b32 v0, s11, v0
	v_cmp_eq_u32_e32 vcc, 0, v0
	s_and_saveexec_b64 s[8:9], vcc
	s_cbranch_execz .LBB0_364
	s_bcnt1_i32_b64 s10, s[10:11]
	v_mov_b32_e32 v1, s10
	v_readlane_b32 s10, v238, 21
	v_readlane_b32 s11, v238, 22
	s_nop 4
	global_atomic_add v1, v81, v1, s[10:11] sc0

.LBB0_372:
	s_waitcnt vmcnt(55)
	v_cvt_pk_bf16_f32 v0, v0, v1
	s_waitcnt vmcnt(53)
	v_cvt_pk_bf16_f32 v1, v2, v3
	s_waitcnt vmcnt(51)
	v_cvt_pk_bf16_f32 v2, v4, v5
	s_waitcnt vmcnt(49)
	v_cvt_pk_bf16_f32 v3, v6, v7
	global_store_dwordx4 v[38:39], v[0:3], off offset:16
	s_waitcnt vmcnt(48)
	s_nop 0
	v_cvt_pk_bf16_f32 v0, v8, v9
	s_waitcnt vmcnt(46)
	v_cvt_pk_bf16_f32 v1, v10, v11
	s_waitcnt vmcnt(44)
	v_cvt_pk_bf16_f32 v2, v12, v13
	s_waitcnt vmcnt(42)
	v_cvt_pk_bf16_f32 v3, v14, v15
	global_store_dwordx4 v[38:39], v[0:3], off offset:32
	s_waitcnt vmcnt(41)
	s_nop 0
	v_cvt_pk_bf16_f32 v0, v16, v17
	s_waitcnt vmcnt(39)
	v_cvt_pk_bf16_f32 v1, v18, v19
	s_waitcnt vmcnt(37)
	v_cvt_pk_bf16_f32 v2, v20, v21
	s_waitcnt vmcnt(35)
	v_cvt_pk_bf16_f32 v3, v22, v23
	global_store_dwordx4 v[38:39], v[0:3], off offset:48
	s_waitcnt vmcnt(34)
	s_nop 0
	v_cvt_pk_bf16_f32 v0, v24, v25
	s_waitcnt vmcnt(32)
	v_cvt_pk_bf16_f32 v1, v26, v27
	s_waitcnt vmcnt(30)
	v_cvt_pk_bf16_f32 v2, v28, v29
	s_waitcnt vmcnt(28)
	v_cvt_pk_bf16_f32 v3, v30, v31
	global_store_dwordx4 v[38:39], v[0:3], off offset:64
	s_waitcnt vmcnt(27)
	s_nop 0
	v_cvt_pk_bf16_f32 v0, v32, v33
	s_waitcnt vmcnt(25)
	v_cvt_pk_bf16_f32 v1, v34, v35
	s_waitcnt vmcnt(23)
	v_cvt_pk_bf16_f32 v2, v36, v37
	s_waitcnt vmcnt(21)
	v_cvt_pk_bf16_f32 v3, v42, v43
	global_store_dwordx4 v[38:39], v[0:3], off offset:80
	s_waitcnt vmcnt(20)
	s_nop 0
	v_cvt_pk_bf16_f32 v0, v50, v51
	s_waitcnt vmcnt(18)
	v_cvt_pk_bf16_f32 v1, v52, v53
	s_waitcnt vmcnt(16)
	v_cvt_pk_bf16_f32 v2, v54, v55
	s_waitcnt vmcnt(14)
	v_cvt_pk_bf16_f32 v3, v56, v57
	global_store_dwordx4 v[38:39], v[0:3], off offset:96
	s_waitcnt vmcnt(13)
	s_nop 0
	v_cvt_pk_bf16_f32 v0, v58, v59
	s_waitcnt vmcnt(11)
	v_cvt_pk_bf16_f32 v1, v60, v61
	s_waitcnt vmcnt(9)
	v_cvt_pk_bf16_f32 v2, v62, v63
	s_waitcnt vmcnt(7)
	v_cvt_pk_bf16_f32 v3, v64, v65
	global_store_dwordx4 v[38:39], v[0:3], off offset:112
	s_add_i32 s98, s98, 1
	s_cmp_lt_u32 s98, 2
	s_cbranch_scc1 .Lcv2_again
